# attention causal-mask blocks in the loop: one v_sub + per element one e64 compare against an inline constant and one cndmask (3 rotating mask registers), window bound checked once per block with the o
# speedup vs baseline: 1.0012x; 1.0012x over previous
.Lat_odd_orig:
	ds_read_b64_tr_b16 v[188:189], v209 offset:0
	ds_read_b64_tr_b16 v[190:191], v209 offset:0x800
	ds_read_b64_tr_b16 v[192:193], v209 offset:0x1000
	ds_read_b64_tr_b16 v[194:195], v209 offset:0x1800
	ds_read_b64_tr_b16 v[234:235], v209 offset:0x2000
	ds_read_b64_tr_b16 v[236:237], v209 offset:0x2800
	ds_read_b64_tr_b16 v[238:239], v209 offset:0x3000
	ds_read_b64_tr_b16 v[240:241], v209 offset:0x3800
	s_nop 0
	s_waitcnt lgkmcnt(6)
	v_mfma_f32_32x32x16_bf16 v[66:81], v[178:181], v[188:191], v[66:81]
	ds_read_b64_tr_b16 v[188:189], v209 offset:0x200
	ds_read_b64_tr_b16 v[190:191], v209 offset:0xa00
	s_waitcnt lgkmcnt(6)
	v_mfma_f32_32x32x16_bf16 v[66:81], v[184:187], v[192:195], v[66:81]
	ds_read_b64_tr_b16 v[192:193], v209 offset:0x1200
	ds_read_b64_tr_b16 v[194:195], v209 offset:0x1a00
	s_waitcnt lgkmcnt(6)
	v_mfma_f32_32x32x16_bf16 v[66:81], v[230:233], v[234:237], v[66:81]
	ds_read_b64_tr_b16 v[234:235], v209 offset:0x2200
	ds_read_b64_tr_b16 v[236:237], v209 offset:0x2a00
	ds_read_b64_tr_b16 v[246:247], v209 offset:0x3200
	ds_read_b64_tr_b16 v[248:249], v209 offset:0x3a00
	s_waitcnt lgkmcnt(8)
	v_mfma_f32_32x32x16_bf16 v[66:81], v[242:245], v[238:241], v[66:81]
	s_waitcnt lgkmcnt(6)
	v_mfma_f32_32x32x16_bf16 v[34:49], v[178:181], v[188:191], v[34:49]
	ds_read_b64_tr_b16 v[188:189], v209 offset:0x400
	ds_read_b64_tr_b16 v[190:191], v209 offset:0xc00
	s_waitcnt lgkmcnt(6)
	v_mfma_f32_32x32x16_bf16 v[34:49], v[184:187], v[192:195], v[34:49]
	ds_read_b64_tr_b16 v[192:193], v209 offset:0x1400
	ds_read_b64_tr_b16 v[194:195], v209 offset:0x1c00
	s_waitcnt lgkmcnt(6)
	v_mfma_f32_32x32x16_bf16 v[34:49], v[230:233], v[234:237], v[34:49]
	ds_read_b64_tr_b16 v[234:235], v209 offset:0x2400
	ds_read_b64_tr_b16 v[236:237], v209 offset:0x2c00
	ds_read_b64_tr_b16 v[238:239], v209 offset:0x3400
	ds_read_b64_tr_b16 v[240:241], v209 offset:0x3c00
	s_waitcnt lgkmcnt(8)
	v_mfma_f32_32x32x16_bf16 v[34:49], v[242:245], v[246:249], v[34:49]
	s_waitcnt lgkmcnt(6)
	v_mfma_f32_32x32x16_bf16 v[18:33], v[178:181], v[188:191], v[18:33]
	ds_read_b64_tr_b16 v[188:189], v209 offset:0x600
	ds_read_b64_tr_b16 v[190:191], v209 offset:0xe00
	s_waitcnt lgkmcnt(6)
	v_mfma_f32_32x32x16_bf16 v[18:33], v[184:187], v[192:195], v[18:33]
	ds_read_b64_tr_b16 v[192:193], v209 offset:0x1600
	ds_read_b64_tr_b16 v[194:195], v209 offset:0x1e00
	s_waitcnt lgkmcnt(6)
	v_mfma_f32_32x32x16_bf16 v[18:33], v[230:233], v[234:237], v[18:33]
	ds_read_b64_tr_b16 v[234:235], v209 offset:0x2600
	ds_read_b64_tr_b16 v[236:237], v209 offset:0x2e00
	ds_read_b64_tr_b16 v[246:247], v209 offset:0x3600
	ds_read_b64_tr_b16 v[248:249], v209 offset:0x3e00
	s_waitcnt lgkmcnt(8)
	v_mfma_f32_32x32x16_bf16 v[18:33], v[242:245], v[238:241], v[18:33]
	s_waitcnt lgkmcnt(6)
	v_mfma_f32_32x32x16_bf16 v[2:17], v[178:181], v[188:191], v[2:17]
	s_cmp_le_i32 s6, s1
	s_cselect_b64 s[6:7], -1, 0
	s_cmp_gt_i32 s38, s8
	s_cselect_b64 s[54:55], -1, 0
	s_and_b64 s[6:7], s[6:7], s[54:55]
	s_and_b64 vcc, exec, s[6:7]
	s_waitcnt lgkmcnt(4)
	v_mfma_f32_32x32x16_bf16 v[2:17], v[184:187], v[192:195], v[2:17]
	s_waitcnt lgkmcnt(2)
	v_mfma_f32_32x32x16_bf16 v[2:17], v[230:233], v[234:237], v[2:17]
	s_waitcnt lgkmcnt(0)
	v_mfma_f32_32x32x16_bf16 v[2:17], v[242:245], v[246:249], v[2:17]
	s_cbranch_vccnz .LBB0_391
	v_subrev_u32_e32 v178, 64, v222
	v_cmp_gt_u32_e32 vcc, s11, v178
	s_nop 1
	v_cndmask_b32_e32 v50, v202, v50, vcc
	v_sub_u32_e32 v178, 0x0000007b, v222
	v_cmp_gt_i32_e32 vcc, 0xfffff03b, v178
	s_cmp_lg_u64 vcc, 0
	s_cbranch_scc1 .Lmask_slow_odd
	v_cmp_le_i32_e64 vcc, v178, 27
	v_cmp_le_i32_e64 s[6:7], v178, 58
	v_cmp_le_i32_e64 s[54:55], v178, 26
	v_cndmask_b32_e64 v82, v202, v82, vcc
	v_cndmask_b32_e64 v51, v202, v51, s[6:7]
	v_cndmask_b32_e64 v83, v202, v83, s[54:55]
	v_cmp_le_i32_e64 vcc, v178, 57
	v_cmp_le_i32_e64 s[6:7], v178, 25
	v_cmp_le_i32_e64 s[54:55], v178, 56
	v_cndmask_b32_e64 v52, v202, v52, vcc
	v_cndmask_b32_e64 v84, v202, v84, s[6:7]
	v_cndmask_b32_e64 v53, v202, v53, s[54:55]
	v_cmp_le_i32_e64 vcc, v178, 24
	v_cmp_le_i32_e64 s[6:7], v178, 51
	v_cmp_le_i32_e64 s[54:55], v178, 19
	v_cndmask_b32_e64 v85, v202, v85, vcc
	v_cndmask_b32_e64 v54, v202, v54, s[6:7]
	v_cndmask_b32_e64 v86, v202, v86, s[54:55]
	v_cmp_le_i32_e64 vcc, v178, 50
	v_cmp_le_i32_e64 s[6:7], v178, 18
	v_cmp_le_i32_e64 s[54:55], v178, 49
	v_cndmask_b32_e64 v55, v202, v55, vcc
	v_cndmask_b32_e64 v87, v202, v87, s[6:7]
	v_cndmask_b32_e64 v56, v202, v56, s[54:55]
	v_cmp_le_i32_e64 vcc, v178, 17
	v_cmp_le_i32_e64 s[6:7], v178, 48
	v_cmp_le_i32_e64 s[54:55], v178, 16
	v_cndmask_b32_e64 v88, v202, v88, vcc
	v_cndmask_b32_e64 v57, v202, v57, s[6:7]
	v_cndmask_b32_e64 v89, v202, v89, s[54:55]
	v_cmp_le_i32_e64 vcc, v178, 43
	v_cmp_le_i32_e64 s[6:7], v178, 11
	v_cmp_le_i32_e64 s[54:55], v178, 42
	v_cndmask_b32_e64 v58, v202, v58, vcc
	v_cndmask_b32_e64 v90, v202, v90, s[6:7]
	v_cndmask_b32_e64 v59, v202, v59, s[54:55]
	v_cmp_le_i32_e64 vcc, v178, 10
	v_cmp_le_i32_e64 s[6:7], v178, 41
	v_cmp_le_i32_e64 s[54:55], v178, 9
	v_cndmask_b32_e64 v91, v202, v91, vcc
	v_cndmask_b32_e64 v60, v202, v60, s[6:7]
	v_cndmask_b32_e64 v92, v202, v92, s[54:55]
	v_cmp_le_i32_e64 vcc, v178, 40
	v_cmp_le_i32_e64 s[6:7], v178, 8
	v_cmp_le_i32_e64 s[54:55], v178, 35
	v_cndmask_b32_e64 v61, v202, v61, vcc
	v_cndmask_b32_e64 v93, v202, v93, s[6:7]
	v_cndmask_b32_e64 v62, v202, v62, s[54:55]
	v_cmp_le_i32_e64 vcc, v178, 3
	v_cmp_le_i32_e64 s[6:7], v178, 34
	v_cmp_le_i32_e64 s[54:55], v178, 2
	v_cndmask_b32_e64 v94, v202, v94, vcc
	v_cndmask_b32_e64 v63, v202, v63, s[6:7]
	v_cndmask_b32_e64 v95, v202, v95, s[54:55]
	v_cmp_le_i32_e64 vcc, v178, 33
	v_cmp_le_i32_e64 s[6:7], v178, 1
	v_cmp_le_i32_e64 s[54:55], v178, 32
	v_cndmask_b32_e64 v64, v202, v64, vcc
	v_cndmask_b32_e64 v96, v202, v96, s[6:7]
	v_cndmask_b32_e64 v65, v202, v65, s[54:55]
	v_cmp_le_i32_e64 vcc, v178, 0
	s_nop 1
	v_cndmask_b32_e64 v97, v202, v97, vcc
	s_branch .LBB0_391
.Lmask_slow_odd:
	v_subrev_u32_e32 v178, 64, v222
	v_cmp_gt_u32_e32 vcc, s11, v178
	v_add_u32_e32 v178, 0xffffefa0, v222
	s_nop 0
	v_cndmask_b32_e32 v50, v202, v50, vcc
	v_cmp_lt_u32_e32 vcc, s68, v178
	v_add_u32_e32 v178, 0xffffefbf, v222
	s_nop 0
	v_cndmask_b32_e32 v82, v202, v82, vcc
	v_cmp_lt_u32_e32 vcc, s68, v178
	v_add_u32_e32 v178, 0xffffef9f, v222
	s_nop 0
	v_cndmask_b32_e32 v51, v202, v51, vcc
	v_cmp_lt_u32_e32 vcc, s68, v178
	v_add_u32_e32 v178, 0xffffefbe, v222
	s_nop 0
	v_cndmask_b32_e32 v83, v202, v83, vcc
	v_cmp_lt_u32_e32 vcc, s68, v178
	v_add_u32_e32 v178, 0xffffef9e, v222
	s_nop 0
	v_cndmask_b32_e32 v52, v202, v52, vcc
	v_cmp_lt_u32_e32 vcc, s68, v178
	v_add_u32_e32 v178, 0xffffefbd, v222
	s_nop 0
	v_cndmask_b32_e32 v84, v202, v84, vcc
	v_cmp_lt_u32_e32 vcc, s68, v178
	v_add_u32_e32 v178, 0xffffef9d, v222
	s_nop 0
	v_cndmask_b32_e32 v53, v202, v53, vcc
	v_cmp_lt_u32_e32 vcc, s68, v178
	v_add_u32_e32 v178, 0xffffefb8, v222
	s_nop 0
	v_cndmask_b32_e32 v85, v202, v85, vcc
	v_cmp_lt_u32_e32 vcc, s68, v178
	v_add_u32_e32 v178, 0xffffef98, v222
	s_nop 0
	v_cndmask_b32_e32 v54, v202, v54, vcc
	v_cmp_lt_u32_e32 vcc, s68, v178
	v_add_u32_e32 v178, 0xffffefb7, v222
	s_nop 0
	v_cndmask_b32_e32 v86, v202, v86, vcc
	v_cmp_lt_u32_e32 vcc, s68, v178
	v_add_u32_e32 v178, 0xffffef97, v222
	s_nop 0
	v_cndmask_b32_e32 v55, v202, v55, vcc
	v_cmp_lt_u32_e32 vcc, s68, v178
	v_add_u32_e32 v178, 0xffffefb6, v222
	s_nop 0
	v_cndmask_b32_e32 v87, v202, v87, vcc
	v_cmp_lt_u32_e32 vcc, s68, v178
	v_add_u32_e32 v178, 0xffffef96, v222
	s_nop 0
	v_cndmask_b32_e32 v56, v202, v56, vcc
	v_cmp_lt_u32_e32 vcc, s68, v178
	v_add_u32_e32 v178, 0xffffefb5, v222
	s_nop 0
	v_cndmask_b32_e32 v88, v202, v88, vcc
	v_cmp_lt_u32_e32 vcc, s68, v178
	v_add_u32_e32 v178, 0xffffef95, v222
	s_nop 0
	v_cndmask_b32_e32 v57, v202, v57, vcc
	v_cmp_lt_u32_e32 vcc, s68, v178
	v_add_u32_e32 v178, 0xffffefb0, v222
	s_nop 0
	v_cndmask_b32_e32 v89, v202, v89, vcc
	v_cmp_lt_u32_e32 vcc, s68, v178
	v_add_u32_e32 v178, 0xffffef90, v222
	s_nop 0
	v_cndmask_b32_e32 v58, v202, v58, vcc
	v_cmp_lt_u32_e32 vcc, s68, v178
	v_add_u32_e32 v178, 0xffffefaf, v222
	s_nop 0
	v_cndmask_b32_e32 v90, v202, v90, vcc
	v_cmp_lt_u32_e32 vcc, s68, v178
	v_add_u32_e32 v178, 0xffffef8f, v222
	s_nop 0
	v_cndmask_b32_e32 v59, v202, v59, vcc
	v_cmp_lt_u32_e32 vcc, s68, v178
	v_add_u32_e32 v178, 0xffffefae, v222
	s_nop 0
	v_cndmask_b32_e32 v91, v202, v91, vcc
	v_cmp_lt_u32_e32 vcc, s68, v178
	v_add_u32_e32 v178, 0xffffef8e, v222
	s_nop 0
	v_cndmask_b32_e32 v60, v202, v60, vcc
	v_cmp_lt_u32_e32 vcc, s68, v178
	v_add_u32_e32 v178, 0xffffefad, v222
	s_nop 0
	v_cndmask_b32_e32 v92, v202, v92, vcc
	v_cmp_lt_u32_e32 vcc, s68, v178
	v_add_u32_e32 v178, 0xffffef8d, v222
	s_nop 0
	v_cndmask_b32_e32 v61, v202, v61, vcc
	v_cmp_lt_u32_e32 vcc, s68, v178
	v_add_u32_e32 v178, 0xffffefa8, v222
	s_nop 0
	v_cndmask_b32_e32 v93, v202, v93, vcc
	v_cmp_lt_u32_e32 vcc, s68, v178
	v_add_u32_e32 v178, 0xffffef88, v222
	s_nop 0
	v_cndmask_b32_e32 v62, v202, v62, vcc
	v_cmp_lt_u32_e32 vcc, s68, v178
	v_add_u32_e32 v178, 0xffffefa7, v222
	s_nop 0
	v_cndmask_b32_e32 v94, v202, v94, vcc
	v_cmp_lt_u32_e32 vcc, s68, v178
	v_add_u32_e32 v178, 0xffffef87, v222
	s_nop 0
	v_cndmask_b32_e32 v63, v202, v63, vcc
	v_cmp_lt_u32_e32 vcc, s68, v178
	v_add_u32_e32 v178, 0xffffefa6, v222
	s_nop 0
	v_cndmask_b32_e32 v95, v202, v95, vcc
	v_cmp_lt_u32_e32 vcc, s68, v178
	v_add_u32_e32 v178, 0xffffef86, v222
	s_nop 0
	v_cndmask_b32_e32 v64, v202, v64, vcc
	v_cmp_lt_u32_e32 vcc, s68, v178
	v_add_u32_e32 v178, 0xffffefa5, v222
	s_nop 0
	v_cndmask_b32_e32 v96, v202, v96, vcc
	v_cmp_lt_u32_e32 vcc, s68, v178
	v_add_u32_e32 v178, 0xffffef85, v222
	s_nop 0
	v_cndmask_b32_e32 v65, v202, v65, vcc
	v_cmp_lt_u32_e32 vcc, s68, v178
	s_nop 1
	v_cndmask_b32_e32 v97, v202, v97, vcc

.Lat_even_orig:
	ds_read_b64_tr_b16 v[230:231], v209 offset:0x4000
	ds_read_b64_tr_b16 v[232:233], v209 offset:0x4800
	ds_read_b64_tr_b16 v[234:235], v209 offset:0x5000
	ds_read_b64_tr_b16 v[236:237], v209 offset:0x5800
	ds_read_b64_tr_b16 v[238:239], v209 offset:0x6000
	ds_read_b64_tr_b16 v[240:241], v209 offset:0x6800
	ds_read_b64_tr_b16 v[242:243], v209 offset:0x7000
	ds_read_b64_tr_b16 v[244:245], v209 offset:0x7800
	s_add_i32 s6, s38, -1
	s_sub_i32 s39, s38, 64
	s_waitcnt lgkmcnt(6)
	v_mfma_f32_32x32x16_bf16 v[66:81], v[178:181], v[230:233], v[66:81]
	ds_read_b64_tr_b16 v[230:231], v209 offset:0x4200
	ds_read_b64_tr_b16 v[232:233], v209 offset:0x4a00
	s_waitcnt lgkmcnt(6)
	v_mfma_f32_32x32x16_bf16 v[66:81], v[182:185], v[234:237], v[66:81]
	ds_read_b64_tr_b16 v[234:235], v209 offset:0x5200
	ds_read_b64_tr_b16 v[236:237], v209 offset:0x5a00
	s_waitcnt lgkmcnt(6)
	v_mfma_f32_32x32x16_bf16 v[66:81], v[186:189], v[238:241], v[66:81]
	ds_read_b64_tr_b16 v[238:239], v209 offset:0x6200
	ds_read_b64_tr_b16 v[240:241], v209 offset:0x6a00
	ds_read_b64_tr_b16 v[246:247], v209 offset:0x7200
	ds_read_b64_tr_b16 v[248:249], v209 offset:0x7a00
	s_waitcnt lgkmcnt(8)
	v_mfma_f32_32x32x16_bf16 v[66:81], v[190:193], v[242:245], v[66:81]
	s_waitcnt lgkmcnt(6)
	v_mfma_f32_32x32x16_bf16 v[34:49], v[178:181], v[230:233], v[34:49]
	ds_read_b64_tr_b16 v[230:231], v209 offset:0x4400
	ds_read_b64_tr_b16 v[232:233], v209 offset:0x4c00
	s_waitcnt lgkmcnt(6)
	v_mfma_f32_32x32x16_bf16 v[34:49], v[182:185], v[234:237], v[34:49]
	ds_read_b64_tr_b16 v[234:235], v209 offset:0x5400
	ds_read_b64_tr_b16 v[236:237], v209 offset:0x5c00
	s_waitcnt lgkmcnt(6)
	v_mfma_f32_32x32x16_bf16 v[34:49], v[186:189], v[238:241], v[34:49]
	ds_read_b64_tr_b16 v[238:239], v209 offset:0x6400
	ds_read_b64_tr_b16 v[240:241], v209 offset:0x6c00
	ds_read_b64_tr_b16 v[242:243], v209 offset:0x7400
	ds_read_b64_tr_b16 v[244:245], v209 offset:0x7c00
	s_waitcnt lgkmcnt(8)
	v_mfma_f32_32x32x16_bf16 v[34:49], v[190:193], v[246:249], v[34:49]
	s_waitcnt lgkmcnt(6)
	v_mfma_f32_32x32x16_bf16 v[18:33], v[178:181], v[230:233], v[18:33]
	ds_read_b64_tr_b16 v[230:231], v209 offset:0x4600
	ds_read_b64_tr_b16 v[232:233], v209 offset:0x4e00
	s_waitcnt lgkmcnt(6)
	v_mfma_f32_32x32x16_bf16 v[18:33], v[182:185], v[234:237], v[18:33]
	ds_read_b64_tr_b16 v[234:235], v209 offset:0x5600
	ds_read_b64_tr_b16 v[236:237], v209 offset:0x5e00
	s_waitcnt lgkmcnt(6)
	v_mfma_f32_32x32x16_bf16 v[18:33], v[186:189], v[238:241], v[18:33]
	ds_read_b64_tr_b16 v[238:239], v209 offset:0x6600
	ds_read_b64_tr_b16 v[240:241], v209 offset:0x6e00
	ds_read_b64_tr_b16 v[246:247], v209 offset:0x7600
	ds_read_b64_tr_b16 v[248:249], v209 offset:0x7e00
	s_waitcnt lgkmcnt(8)
	v_mfma_f32_32x32x16_bf16 v[18:33], v[190:193], v[242:245], v[18:33]
	s_waitcnt lgkmcnt(6)
	v_mfma_f32_32x32x16_bf16 v[2:17], v[178:181], v[230:233], v[2:17]
	s_cmp_le_i32 s6, s1
	s_cselect_b64 s[6:7], -1, 0
	s_cmp_gt_i32 s39, s8
	s_cselect_b64 s[56:57], -1, 0
	s_and_b64 s[6:7], s[6:7], s[56:57]
	s_and_b64 vcc, exec, s[6:7]
	s_waitcnt lgkmcnt(4)
	v_mfma_f32_32x32x16_bf16 v[2:17], v[182:185], v[234:237], v[2:17]
	s_waitcnt lgkmcnt(2)
	v_mfma_f32_32x32x16_bf16 v[2:17], v[186:189], v[238:241], v[2:17]
	s_waitcnt lgkmcnt(0)
	v_mfma_f32_32x32x16_bf16 v[2:17], v[190:193], v[246:249], v[2:17]
	s_cbranch_vccnz .LBB0_399
	v_cmp_gt_u32_e32 vcc, s11, v222
	s_nop 1
	v_cndmask_b32_e32 v114, v202, v114, vcc
	v_sub_u32_e32 v178, 0x0000003b, v222
	v_cmp_gt_i32_e32 vcc, 0xfffff03b, v178
	s_cmp_lg_u64 vcc, 0
	s_cbranch_scc1 .Lmask_slow_even
	v_cmp_le_i32_e64 vcc, v178, 27
	v_cmp_le_i32_e64 s[6:7], v178, 58
	v_cmp_le_i32_e64 s[56:57], v178, 26
	v_cndmask_b32_e64 v98, v202, v98, vcc
	v_cndmask_b32_e64 v115, v202, v115, s[6:7]
	v_cndmask_b32_e64 v99, v202, v99, s[56:57]
	v_cmp_le_i32_e64 vcc, v178, 57
	v_cmp_le_i32_e64 s[6:7], v178, 25
	v_cmp_le_i32_e64 s[56:57], v178, 56
	v_cndmask_b32_e64 v116, v202, v116, vcc
	v_cndmask_b32_e64 v100, v202, v100, s[6:7]
	v_cndmask_b32_e64 v117, v202, v117, s[56:57]
	v_cmp_le_i32_e64 vcc, v178, 24
	v_cmp_le_i32_e64 s[6:7], v178, 51
	v_cmp_le_i32_e64 s[56:57], v178, 19
	v_cndmask_b32_e64 v101, v202, v101, vcc
	v_cndmask_b32_e64 v118, v202, v118, s[6:7]
	v_cndmask_b32_e64 v102, v202, v102, s[56:57]
	v_cmp_le_i32_e64 vcc, v178, 50
	v_cmp_le_i32_e64 s[6:7], v178, 18
	v_cmp_le_i32_e64 s[56:57], v178, 49
	v_cndmask_b32_e64 v119, v202, v119, vcc
	v_cndmask_b32_e64 v103, v202, v103, s[6:7]
	v_cndmask_b32_e64 v120, v202, v120, s[56:57]
	v_cmp_le_i32_e64 vcc, v178, 17
	v_cmp_le_i32_e64 s[6:7], v178, 48
	v_cmp_le_i32_e64 s[56:57], v178, 16
	v_cndmask_b32_e64 v104, v202, v104, vcc
	v_cndmask_b32_e64 v121, v202, v121, s[6:7]
	v_cndmask_b32_e64 v105, v202, v105, s[56:57]
	v_cmp_le_i32_e64 vcc, v178, 43
	v_cmp_le_i32_e64 s[6:7], v178, 11
	v_cmp_le_i32_e64 s[56:57], v178, 42
	v_cndmask_b32_e64 v122, v202, v122, vcc
	v_cndmask_b32_e64 v106, v202, v106, s[6:7]
	v_cndmask_b32_e64 v123, v202, v123, s[56:57]
	v_cmp_le_i32_e64 vcc, v178, 10
	v_cmp_le_i32_e64 s[6:7], v178, 41
	v_cmp_le_i32_e64 s[56:57], v178, 9
	v_cndmask_b32_e64 v107, v202, v107, vcc
	v_cndmask_b32_e64 v124, v202, v124, s[6:7]
	v_cndmask_b32_e64 v108, v202, v108, s[56:57]
	v_cmp_le_i32_e64 vcc, v178, 40
	v_cmp_le_i32_e64 s[6:7], v178, 8
	v_cmp_le_i32_e64 s[56:57], v178, 35
	v_cndmask_b32_e64 v125, v202, v125, vcc
	v_cndmask_b32_e64 v109, v202, v109, s[6:7]
	v_cndmask_b32_e64 v126, v202, v126, s[56:57]
	v_cmp_le_i32_e64 vcc, v178, 3
	v_cmp_le_i32_e64 s[6:7], v178, 34
	v_cmp_le_i32_e64 s[56:57], v178, 2
	v_cndmask_b32_e64 v110, v202, v110, vcc
	v_cndmask_b32_e64 v127, v202, v127, s[6:7]
	v_cndmask_b32_e64 v111, v202, v111, s[56:57]
	v_cmp_le_i32_e64 vcc, v178, 33
	v_cmp_le_i32_e64 s[6:7], v178, 1
	v_cmp_le_i32_e64 s[56:57], v178, 32
	v_cndmask_b32_e64 v128, v202, v128, vcc
	v_cndmask_b32_e64 v112, v202, v112, s[6:7]
	v_cndmask_b32_e64 v129, v202, v129, s[56:57]
	v_cmp_le_i32_e64 vcc, v178, 0
	s_nop 1
	v_cndmask_b32_e64 v113, v202, v113, vcc
	s_branch .LBB0_399
.Lmask_slow_even:
	v_cmp_gt_u32_e32 vcc, s11, v222
	v_add_u32_e32 v178, 0xffffefe0, v222
	s_nop 0
	v_cndmask_b32_e32 v114, v202, v114, vcc
	v_cmp_lt_u32_e32 vcc, s68, v178
	v_add_u32_e32 v178, 0xffffefff, v222
	s_nop 0
	v_cndmask_b32_e32 v98, v202, v98, vcc
	v_cmp_lt_u32_e32 vcc, s68, v178
	v_add_u32_e32 v178, 0xffffefdf, v222
	s_nop 0
	v_cndmask_b32_e32 v115, v202, v115, vcc
	v_cmp_lt_u32_e32 vcc, s68, v178
	v_add_u32_e32 v178, 0xffffeffe, v222
	s_nop 0
	v_cndmask_b32_e32 v99, v202, v99, vcc
	v_cmp_lt_u32_e32 vcc, s68, v178
	v_add_u32_e32 v178, 0xffffefde, v222
	s_nop 0
	v_cndmask_b32_e32 v116, v202, v116, vcc
	v_cmp_lt_u32_e32 vcc, s68, v178
	v_add_u32_e32 v178, 0xffffeffd, v222
	s_nop 0
	v_cndmask_b32_e32 v100, v202, v100, vcc
	v_cmp_lt_u32_e32 vcc, s68, v178
	v_add_u32_e32 v178, 0xffffefdd, v222
	s_nop 0
	v_cndmask_b32_e32 v117, v202, v117, vcc
	v_cmp_lt_u32_e32 vcc, s68, v178
	v_add_u32_e32 v178, 0xffffeff8, v222
	s_nop 0
	v_cndmask_b32_e32 v101, v202, v101, vcc
	v_cmp_lt_u32_e32 vcc, s68, v178
	v_add_u32_e32 v178, 0xffffefd8, v222
	s_nop 0
	v_cndmask_b32_e32 v118, v202, v118, vcc
	v_cmp_lt_u32_e32 vcc, s68, v178
	v_add_u32_e32 v178, 0xffffeff7, v222
	s_nop 0
	v_cndmask_b32_e32 v102, v202, v102, vcc
	v_cmp_lt_u32_e32 vcc, s68, v178
	v_add_u32_e32 v178, 0xffffefd7, v222
	s_nop 0
	v_cndmask_b32_e32 v119, v202, v119, vcc
	v_cmp_lt_u32_e32 vcc, s68, v178
	v_add_u32_e32 v178, 0xffffeff6, v222
	s_nop 0
	v_cndmask_b32_e32 v103, v202, v103, vcc
	v_cmp_lt_u32_e32 vcc, s68, v178
	v_add_u32_e32 v178, 0xffffefd6, v222
	s_nop 0
	v_cndmask_b32_e32 v120, v202, v120, vcc
	v_cmp_lt_u32_e32 vcc, s68, v178
	v_add_u32_e32 v178, 0xffffeff5, v222
	s_nop 0
	v_cndmask_b32_e32 v104, v202, v104, vcc
	v_cmp_lt_u32_e32 vcc, s68, v178
	v_add_u32_e32 v178, 0xffffefd5, v222
	s_nop 0
	v_cndmask_b32_e32 v121, v202, v121, vcc
	v_cmp_lt_u32_e32 vcc, s68, v178
	v_add_u32_e32 v178, 0xffffeff0, v222
	s_nop 0
	v_cndmask_b32_e32 v105, v202, v105, vcc
	v_cmp_lt_u32_e32 vcc, s68, v178
	v_add_u32_e32 v178, 0xffffefd0, v222
	s_nop 0
	v_cndmask_b32_e32 v122, v202, v122, vcc
	v_cmp_lt_u32_e32 vcc, s68, v178
	v_add_u32_e32 v178, 0xffffefef, v222
	s_nop 0
	v_cndmask_b32_e32 v106, v202, v106, vcc
	v_cmp_lt_u32_e32 vcc, s68, v178
	v_add_u32_e32 v178, 0xffffefcf, v222
	s_nop 0
	v_cndmask_b32_e32 v123, v202, v123, vcc
	v_cmp_lt_u32_e32 vcc, s68, v178
	v_add_u32_e32 v178, 0xffffefee, v222
	s_nop 0
	v_cndmask_b32_e32 v107, v202, v107, vcc
	v_cmp_lt_u32_e32 vcc, s68, v178
	v_add_u32_e32 v178, 0xffffefce, v222
	s_nop 0
	v_cndmask_b32_e32 v124, v202, v124, vcc
	v_cmp_lt_u32_e32 vcc, s68, v178
	v_add_u32_e32 v178, 0xffffefed, v222
	s_nop 0
	v_cndmask_b32_e32 v108, v202, v108, vcc
	v_cmp_lt_u32_e32 vcc, s68, v178
	v_add_u32_e32 v178, 0xffffefcd, v222
	s_nop 0
	v_cndmask_b32_e32 v125, v202, v125, vcc
	v_cmp_lt_u32_e32 vcc, s68, v178
	v_add_u32_e32 v178, 0xffffefe8, v222
	s_nop 0
	v_cndmask_b32_e32 v109, v202, v109, vcc
	v_cmp_lt_u32_e32 vcc, s68, v178
	v_add_u32_e32 v178, 0xffffefc8, v222
	s_nop 0
	v_cndmask_b32_e32 v126, v202, v126, vcc
	v_cmp_lt_u32_e32 vcc, s68, v178
	v_add_u32_e32 v178, 0xffffefe7, v222
	s_nop 0
	v_cndmask_b32_e32 v110, v202, v110, vcc
	v_cmp_lt_u32_e32 vcc, s68, v178
	v_add_u32_e32 v178, 0xffffefc7, v222
	s_nop 0
	v_cndmask_b32_e32 v127, v202, v127, vcc
	v_cmp_lt_u32_e32 vcc, s68, v178
	v_add_u32_e32 v178, 0xffffefe6, v222
	s_nop 0
	v_cndmask_b32_e32 v111, v202, v111, vcc
	v_cmp_lt_u32_e32 vcc, s68, v178
	v_add_u32_e32 v178, 0xffffefc6, v222
	s_nop 0
	v_cndmask_b32_e32 v128, v202, v128, vcc
	v_cmp_lt_u32_e32 vcc, s68, v178
	v_add_u32_e32 v178, 0xffffefe5, v222
	s_nop 0
	v_cndmask_b32_e32 v112, v202, v112, vcc
	v_cmp_lt_u32_e32 vcc, s68, v178
	v_add_u32_e32 v178, 0xffffefc5, v222
	s_nop 0
	v_cndmask_b32_e32 v129, v202, v129, vcc
	v_cmp_lt_u32_e32 vcc, s68, v178
	s_nop 1
	v_cndmask_b32_e32 v113, v202, v113, vcc
